# phase 0: norm_w row-scale vector hoisted out of the per-row loop (no per-quarter load+drain); phase-2 worker count derived from grid size
# baseline (speedup 1.0000x reference)
; __device__ __forceinline__ int ltid() { int t = threadIdx.x; asm volatile("" : "+v"(t)); return t; }
; __device__ __forceinline__ void phase0(const Params& p, unsigned char* smem) {
;   u16* hn = (u16*)p.out; u16* wtin = hn + (size_t)NTOK * DM;
;   u16* w3 = (u16*)(p.ws + OFF_W3);
;   const int tid = ltid(), lane = tid & 63, wave = tid >> 6;
;   constexpr int N_HN = NTOK / 4;
;   constexpr int NT_IN = 161;
;   constexpr int N_TR = 16 * NT_IN + 3 * 256;
;   constexpr int N_MISC = 16;
;   for (int it = blockIdx.x; it < N_HN + N_TR + N_MISC; it += gridDim.x) {
;     if (it < N_HN) {
;       int row = it * 4 + wave; int b = row / LTOK, pos = row - b * LTOK;
;       const float* src = pos < NMETA ? p.meta + pos * DM : p.x + ((size_t)b * SEQ + pos - NMETA) * DM;
;       float4 v[4]; float ss = 0.f;
; #pragma unroll
;       for (int i = 0; i < 4; ++i) { v[i] = ((const float4*)src)[lane + 64 * i]; ss += v[i].x * v[i].x + v[i].y * v[i].y + v[i].z * v[i].z + v[i].w * v[i].w; }
;       ss = wave_sum(ss);
;       float rs = rsqrtf(ss * (1.f / 1024.f) + 1e-6f);
; #pragma unroll
;       for (int i = 0; i < 4; ++i) {
;         float4 w = ((const float4*)p.norm_w)[lane + 64 * i];
_Z4mega6Params:
	s_load_dwordx4 s[48:51], s[0:1], 0x88
	s_load_dword s3, s[0:1], 0x98
	s_add_u32 s16, s0, 0x98
	s_mov_b32 s89, s2
	s_addc_u32 s17, s1, 0
	v_and_b32_e32 v218, 0x3ff, v0
	s_movk_i32 s2, 0x3ff
	v_mov_b32_e32 v2, v218
	s_cmpk_gt_i32 s89, 0x1d27
	v_mbcnt_lo_u32_b32 v219, -1, 0
	s_cbranch_scc1 .LBB0_73
	s_waitcnt lgkmcnt(0)
	s_add_u32 s18, s48, 0x2010000
	s_addc_u32 s19, s49, 0
	s_add_u32 s33, s50, 0xe81d000
	v_lshlrev_b32_e32 v5, 1, v2
	s_addc_u32 s40, s51, 0
	v_and_b32_e32 v22, 62, v5
	v_ashrrev_i32_e32 v5, 5, v2
	v_ashrrev_i32_e32 v1, 6, v2
	v_ashrrev_i32_e32 v3, 31, v2
	s_add_u32 s22, s0, 24
	s_movk_i32 s10, 0x104
	v_mul_u32_u24_e32 v8, 0x104, v22
	v_lshlrev_b32_e32 v9, 2, v5
	s_addc_u32 s23, s1, 0
	v_mul_lo_u32 v24, v1, s10
	v_add3_u32 v44, 16, v8, v9
	v_lshl_add_u64 v[8:9], v[2:3], 2, s[50:51]
	s_load_dwordx8 s[52:59], s[0:1], 0x20
	s_mov_b64 s[10:11], 0xf223000
	s_add_u32 s24, s50, 0x3018000
	v_lshl_add_u64 v[8:9], v[8:9], 0, s[10:11]
	s_load_dwordx4 s[12:15], s[0:1], 0x0
	s_load_dwordx2 s[10:11], s[0:1], 0x10
	s_addc_u32 s25, s51, 0
	v_and_b32_e32 v4, 63, v2
	s_add_u32 s26, s50, 0x4054020
	v_mov_b32_e32 v7, 0
	v_lshlrev_b32_e32 v6, 2, v4
	s_addc_u32 s27, s51, 0
	v_add_u32_e32 v23, 16, v6
	s_waitcnt lgkmcnt(0)
	v_lshl_add_u64 v[10:11], s[52:53], 0, v[6:7]
	v_lshl_add_u64 v[12:13], s[54:55], 0, v[6:7]
	v_lshl_add_u64 v[14:15], s[56:57], 0, v[6:7]
	v_lshl_add_u64 v[16:17], s[58:59], 0, v[6:7]
	s_add_u32 s28, s50, 0xf223040
	v_lshlrev_b32_e32 v6, 4, v4
	v_lshl_add_u32 v3, s89, 8, v2
	s_addc_u32 s29, s51, 0
	v_lshl_add_u64 v[18:19], s[10:11], 0, v[6:7]
	global_load_dwordx4 v[100:103], v[18:19], off
	global_load_dwordx4 v[104:107], v[18:19], off offset:1024
	global_load_dwordx4 v[108:111], v[18:19], off offset:2048
	global_load_dwordx4 v[112:115], v[18:19], off offset:3072
	v_add_u32_e32 v45, 0xffe2e800, v3
	s_lshl_b32 s41, s3, 8
	v_lshlrev_b32_e32 v6, 3, v4
	s_mov_b32 s30, 0xffff0000
	v_cmp_gt_i32_e64 s[8:9], 16, v2
	v_cmp_eq_u32_e64 s[4:5], 1, v1
	s_mov_b32 s21, 0
	v_cmp_eq_u32_e64 s[6:7], 0, v4
	v_add_u32_e32 v32, 16, v1
	v_add_u32_e32 v33, 20, v1
	v_add_u32_e32 v34, 24, v1
	v_add_u32_e32 v35, 28, v1
	v_add_u32_e32 v36, 32, v1
	v_add_u32_e32 v37, 36, v1
	v_add_u32_e32 v38, 40, v1
	v_add_u32_e32 v39, 44, v1
	v_add_u32_e32 v40, 48, v1
	v_add_u32_e32 v41, 52, v1
	v_add_u32_e32 v42, 56, v1
	v_add_u32_e32 v43, 60, v1
	s_sub_i32 s42, 0, s41
	v_lshl_add_u64 v[20:21], s[48:49], 0, v[6:7]
	s_mov_b32 s43, 0x1d27ff
	v_sub_u32_e32 v46, 0x1d27ff, v3
	s_mov_b32 s44, 0xc000
	s_movk_i32 s45, 0xfff
	s_mov_b32 s46, 0x2aaaaaab
	s_movk_i32 s47, 0xa000
	s_mov_b32 s52, 0xafff
	s_movk_i32 s53, 0xffe8
	s_movk_i32 s54, 0x4080
	s_movk_i32 s55, 0x70
	v_lshlrev_b32_e32 v6, 1, v22
	s_mov_b32 s56, 0x7fc01ff1
	s_movk_i32 s57, 0xdff0
	s_mov_b32 s31, -1
	v_lshlrev_b32_e32 v22, 4, v4
	v_mov_b32_e32 v47, 0x358637bd
	s_mov_b32 s58, 0x800000
	v_mbcnt_hi_u32_b32 v48, -1, v219
	v_add_u32_e32 v49, v23, v24
	v_mov_b32_e32 v50, v45
	s_mov_b32 s59, 0
	s_mov_b32 s60, s89
	s_waitcnt vmcnt(0)
	s_branch .LBB0_4
; __device__ __forceinline__ unsigned cvtpk(float lo, float hi) { f32x2_t v = {lo, hi}; bf16x2_t b = __builtin_convertvector(v, bf16x2_t); return __builtin_bit_cast(unsigned, b); }
; __device__ __forceinline__ void phase0(const Params& p, unsigned char* smem) {
;     ...
;       int row = it * 4 + wave; int b = row / LTOK, pos = row - b * LTOK;
;       const float* src = pos < NMETA ? p.meta + pos * DM : p.x + ((size_t)b * SEQ + pos - NMETA) * DM;
;       float4 v[4]; float ss = 0.f;
; #pragma unroll
;       for (int i = 0; i < 4; ++i) { v[i] = ((const float4*)src)[lane + 64 * i]; ss += v[i].x * v[i].x + v[i].y * v[i].y + v[i].z * v[i].z + v[i].w * v[i].w; }
;       ss = wave_sum(ss);
;       float rs = rsqrtf(ss * (1.f / 1024.f) + 1e-6f);
; #pragma unroll
;       for (int i = 0; i < 4; ++i) {
;         float4 w = ((const float4*)p.norm_w)[lane + 64 * i];
;         uint2 o; o.x = cvtpk(v[i].x * rs * w.x, v[i].y * rs * w.y); o.y = cvtpk(v[i].z * rs * w.z, v[i].w * rs * w.w);
;         ((uint2*)(hn + (size_t)row * DM))[lane + 64 * i] = o;
;       }
.LBB0_2:
	s_or_b64 exec, exec, s[10:11]
	v_mov_b32_e32 v23, v7
	v_lshl_add_u64 v[30:31], v[28:29], 0, v[22:23]
	global_load_dwordx4 v[26:29], v[30:31], off
	global_load_dwordx4 v[52:55], v[30:31], off offset:1024
	global_load_dwordx4 v[56:59], v[30:31], off offset:2048
	global_load_dwordx4 v[60:63], v[30:31], off offset:3072
	v_and_b32_e32 v23, 64, v48
	v_xor_b32_e32 v25, 32, v48
	v_add_u32_e32 v23, 64, v23
	v_cmp_lt_i32_e32 vcc, v25, v23
	s_waitcnt vmcnt(3)
	v_mov_b32_e32 v72, v27
	s_waitcnt vmcnt(2)
	v_mov_b32_e32 v73, v53
	v_mov_b32_e32 v70, v26
	v_mov_b32_e32 v71, v52
	s_waitcnt vmcnt(1)
	v_mov_b32_e32 v80, v57
	s_waitcnt vmcnt(0)
	v_mov_b32_e32 v81, v61
	v_pk_mul_f32 v[72:73], v[72:73], v[72:73]
	v_mov_b32_e32 v30, v28
	v_mov_b32_e32 v31, v54
	v_mov_b32_e32 v78, v56
	v_mov_b32_e32 v79, v60
	v_pk_mul_f32 v[80:81], v[80:81], v[80:81]
	v_pk_fma_f32 v[70:71], v[70:71], v[70:71], v[72:73]
	v_mov_b32_e32 v68, v29
	v_mov_b32_e32 v69, v55
	v_mov_b32_e32 v74, v58
	v_mov_b32_e32 v75, v62
	v_pk_fma_f32 v[72:73], v[78:79], v[78:79], v[80:81]
	v_pk_fma_f32 v[30:31], v[30:31], v[30:31], v[70:71]
	v_mov_b32_e32 v76, v59
	v_mov_b32_e32 v77, v63
	v_pk_fma_f32 v[70:71], v[74:75], v[74:75], v[72:73]
	v_pk_fma_f32 v[30:31], v[68:69], v[68:69], v[30:31]
	v_pk_fma_f32 v[68:69], v[76:77], v[76:77], v[70:71]
	v_add_f32_e32 v30, v30, v31
	v_cndmask_b32_e32 v25, v48, v25, vcc
	v_add_f32_e32 v30, v30, v68
	v_lshlrev_b32_e32 v25, 2, v25
	v_add_f32_e32 v30, v30, v69
	ds_bpermute_b32 v25, v25, v30
	v_xor_b32_e32 v31, 16, v48
	v_cmp_lt_i32_e32 vcc, v31, v23
	s_waitcnt lgkmcnt(0)
	v_add_f32_e32 v25, v30, v25
	v_cndmask_b32_e32 v31, v48, v31, vcc
	v_lshlrev_b32_e32 v31, 2, v31
	ds_bpermute_b32 v30, v31, v25
	v_xor_b32_e32 v31, 8, v48
	v_cmp_lt_i32_e32 vcc, v31, v23
	s_waitcnt lgkmcnt(0)
	v_add_f32_e32 v25, v25, v30
	v_cndmask_b32_e32 v31, v48, v31, vcc
	v_lshlrev_b32_e32 v31, 2, v31
	ds_bpermute_b32 v30, v31, v25
	v_xor_b32_e32 v31, 4, v48
	v_cmp_lt_i32_e32 vcc, v31, v23
	s_waitcnt lgkmcnt(0)
	v_add_f32_e32 v25, v25, v30
	v_cndmask_b32_e32 v31, v48, v31, vcc
	v_lshlrev_b32_e32 v31, 2, v31
	ds_bpermute_b32 v30, v31, v25
	v_xor_b32_e32 v31, 2, v48
	v_cmp_lt_i32_e32 vcc, v31, v23
	s_waitcnt lgkmcnt(0)
	v_add_f32_e32 v25, v25, v30
	v_cndmask_b32_e32 v31, v48, v31, vcc
	v_lshlrev_b32_e32 v31, 2, v31
	ds_bpermute_b32 v30, v31, v25
	v_xor_b32_e32 v31, 1, v48
	v_cmp_lt_i32_e32 vcc, v31, v23
	s_waitcnt lgkmcnt(0)
	v_add_f32_e32 v25, v25, v30
	v_cndmask_b32_e32 v23, v48, v31, vcc
	v_lshlrev_b32_e32 v23, 2, v23
	ds_bpermute_b32 v23, v23, v25
	s_waitcnt lgkmcnt(0)
	v_add_f32_e32 v23, v25, v23
	v_fmamk_f32 v23, v23, 0x3a800000, v47
	v_mul_f32_e32 v25, 0x4b800000, v23
	v_cmp_gt_f32_e32 vcc, s58, v23
	s_nop 1
	v_cndmask_b32_e32 v23, v23, v25, vcc
	v_rsq_f32_e32 v23, v23
	v_ashrrev_i32_e32 v25, 31, v24
	v_lshlrev_b64 v[24:25], 11, v[24:25]
	v_lshl_add_u64 v[30:31], v[20:21], 0, v[24:25]
	v_mul_f32_e32 v24, 0x45800000, v23
	v_cndmask_b32_e32 v68, v23, v24, vcc
	v_pk_mul_f32 v[24:25], v[26:27], v[68:69] op_sel_hi:[1,0]
	v_pk_mul_f32 v[26:27], v[28:29], v[68:69] op_sel_hi:[1,0]
	v_pk_mul_f32 v[24:25], v[100:101], v[24:25]
	v_pk_mul_f32 v[26:27], v[102:103], v[26:27]
	v_cvt_pk_bf16_f32 v24, v24, v25
	v_cvt_pk_bf16_f32 v25, v26, v27
	global_store_dwordx2 v[30:31], v[24:25], off
	v_pk_mul_f32 v[28:29], v[52:53], v[68:69] op_sel_hi:[1,0]
	v_pk_mul_f32 v[52:53], v[54:55], v[68:69] op_sel_hi:[1,0]
	v_pk_mul_f32 v[24:25], v[104:105], v[28:29]
	v_pk_mul_f32 v[26:27], v[106:107], v[52:53]
	v_cvt_pk_bf16_f32 v24, v24, v25
	v_cvt_pk_bf16_f32 v25, v26, v27
	global_store_dwordx2 v[30:31], v[24:25], off offset:512
	v_pk_mul_f32 v[28:29], v[56:57], v[68:69] op_sel_hi:[1,0]
	v_pk_mul_f32 v[52:53], v[58:59], v[68:69] op_sel_hi:[1,0]
	v_pk_mul_f32 v[24:25], v[28:29], v[108:109]
	v_pk_mul_f32 v[26:27], v[52:53], v[110:111]
	v_cvt_pk_bf16_f32 v24, v24, v25
	v_cvt_pk_bf16_f32 v25, v26, v27
	global_store_dwordx2 v[30:31], v[24:25], off offset:1024
	v_pk_mul_f32 v[28:29], v[60:61], v[68:69] op_sel_hi:[1,0]
	v_pk_mul_f32 v[52:53], v[62:63], v[68:69] op_sel_hi:[1,0]
	v_pk_mul_f32 v[24:25], v[28:29], v[112:113]
	v_pk_mul_f32 v[26:27], v[52:53], v[114:115]
	v_cvt_pk_bf16_f32 v24, v24, v25
	v_cvt_pk_bf16_f32 v25, v26, v27
	global_store_dwordx2 v[30:31], v[24:25], off offset:1536

; __device__ __forceinline__ float bflo(unsigned v) { return __uint_as_float(v << 16); }
; __device__ __forceinline__ float bfhi(unsigned v) { return __uint_as_float(v & 0xffff0000u); }
; template <bool SIGNAL>
; __device__ __forceinline__ void phase2(const Params& p, unsigned char* smem, const int lo, const int hi, const int worker, const int nworkers) {
;     ...
;   for (int idx2 = lo + worker; idx2 < hi; idx2 += nworkers) {
;     const int bh = idx2 & 15, c = idx2 >> 4; const int it = bh * NCH + c; const int h = bh & 7;
;     if (wave == 0) {
;       const bool pad = (c == 0 && lane < 48);
;       float g = pad ? 0.f : GG[(size_t)bh * LPAD + c * 64 + lane];
;       float be = pad ? 0.f : BETA[(size_t)bh * LPAD + c * 64 + lane];
; #pragma unroll
;       for (int o = 1; o < 64; o <<= 1) { float t = __shfl_up(g, o); if (lane >= o) g += t; }
;       sgc[lane] = g; sbeta[lane] = be;
;     }
;     for (int wi = 0; wi < 3; ++wi) {
;       const int which = wi == 0 ? 2 : wi - 1;
;       u16* X = DX + ((size_t)it * 3 + which) * 8192;
;       const u16* H = HALO + ((size_t)(it - 1) * 3 + which) * 384;
;       {
;         u32x4 ld[5];
; #pragma unroll
;         for (int i = 0; i < 5; ++i) {
;           const int idx = tid + 256 * i; const int rr = idx >> 4, c8 = (idx & 15) * 8; const int r = rr - 3;
;           const bool zero = (idx >= 67 * 16) || (c == 0 && r < 48);
;           const u16* srcp = (r < 0) ? (H + rr * 128 + c8) : (X + r * 128 + c8);
;           u32x4 z = {0u, 0u, 0u, 0u};
;           ld[i] = zero ? z : *(const u32x4*)srcp;
;         }
; #pragma unroll
;         for (int i = 0; i < 5; ++i) {
;           const int idx = tid + 256 * i; const int rr = idx >> 4, c8 = (idx & 15) * 8;
;           if (idx < 67 * 16) {
;             float4 a = make_float4(bflo(ld[i].x), bfhi(ld[i].x), bflo(ld[i].y), bfhi(ld[i].y));
;             float4 b = make_float4(bflo(ld[i].z), bfhi(ld[i].z), bflo(ld[i].w), bfhi(ld[i].w));
;             *(float4*)(sin + rr * 128 + c8) = a; *(float4*)(sin + rr * 128 + c8 + 4) = b;
;           }
;         }
.LBB0_250:
	s_or_b64 exec, exec, s[4:5]
	v_mov_b32_e32 v220, v218
	v_writelane_b32 v247, s12, 0
	s_cmp_gt_u32 s89, 15
	s_mov_b64 s[4:5], -1
	v_writelane_b32 v247, s13, 1
	s_barrier
	s_cbranch_scc0 .LBB0_311
	s_add_i32 s84, s89, -16
	v_mov_b32_e32 v32, v218
	s_add_i32 s2, s3, -16
	s_min_u32 s2, s2, 0xf8
	s_cmp_ge_i32 s84, s2
	v_writelane_b32 v247, s73, 2
	s_cbranch_scc1 .LBB0_310
	s_load_dwordx2 s[6:7], s[0:1], 0x90
	v_lshlrev_b32_e32 v7, 3, v32
	v_and_b32_e32 v0, 0x78, v7
	v_mov_b32_e32 v35, 0
	v_lshlrev_b32_e32 v34, 1, v0
	s_waitcnt lgkmcnt(0)
	s_add_u32 s85, s6, 0x6090000
	s_addc_u32 s86, s7, 0
	s_add_u32 s2, s6, 0xee1d000
	v_writelane_b32 v247, s2, 3
	s_addc_u32 s2, s7, 0
	v_writelane_b32 v247, s2, 4
	s_add_u32 s2, s6, 0xee9e000
	v_writelane_b32 v247, s2, 5
	s_addc_u32 s2, s7, 0
	v_writelane_b32 v247, s2, 6
	s_add_u32 s2, s6, 0xc5d9000
	v_writelane_b32 v247, s2, 7
	s_addc_u32 s2, s7, 0
	v_lshl_add_u64 v[4:5], s[6:7], 0, v[34:35]
	s_mov_b64 s[12:13], 0xc150000
	v_writelane_b32 v247, s2, 8
	v_lshl_add_u64 v[36:37], v[4:5], 0, s[12:13]
	v_cmp_gt_i32_e64 s[12:13], 64, v32
	v_and_b32_e32 v39, 63, v32
	v_ashrrev_i32_e32 v2, 6, v32
	v_writelane_b32 v247, s12, 9
	v_and_b32_e32 v1, 31, v32
	v_and_b32_e32 v38, 56, v7
	v_writelane_b32 v247, s13, 10
	v_cmp_eq_u32_e64 s[12:13], 0, v32
	v_lshlrev_b32_e32 v7, 5, v2
	v_and_or_b32 v1, v7, 32, v1
	v_writelane_b32 v247, s12, 11
	s_movk_i32 s11, 0x110
	v_ashrrev_i32_e32 v13, 2, v32
	v_writelane_b32 v247, s13, 12
	v_cmp_eq_u32_e64 s[12:13], 0, v39
	s_movk_i32 s8, 0xffe0
	v_bfe_u32 v6, v32, 5, 1
	v_writelane_b32 v247, s12, 13
	v_mad_u32_u24 v11, v1, s11, 16
	v_and_b32_e32 v14, 0xffffffe0, v13
	v_writelane_b32 v247, s13, 14
	v_cmp_gt_u32_e64 s[12:13], 2, v39
	v_bfi_b32 v13, s8, v13, v32
	s_movk_i32 s8, 0xfef4
	v_writelane_b32 v247, s12, 15
	v_mul_u32_u24_e32 v4, 0x118, v39
	v_lshlrev_b32_e32 v5, 3, v39
	v_writelane_b32 v247, s13, 16
	v_cmp_gt_u32_e64 s[12:13], 4, v39
	v_lshl_add_u32 v10, v38, 1, 16
	v_lshlrev_b32_e32 v12, 4, v6
	v_writelane_b32 v247, s12, 17
	v_lshl_or_b32 v20, v6, 2, v14
	v_mad_i32_i24 v6, v1, s8, v11
	v_writelane_b32 v247, s13, 18
	v_cmp_gt_u32_e64 s[12:13], 8, v39
	s_movk_i32 s8, 0x10e
	v_add3_u32 v9, 16, v5, v4
	v_writelane_b32 v247, s12, 19
	v_add_u32_e32 v108, v11, v12
	v_lshlrev_b32_e32 v11, 4, v39
	v_writelane_b32 v247, s13, 20
	v_cmp_gt_u32_e64 s[12:13], 16, v39
	v_mad_u32_u24 v21, v38, s8, v10
	s_movk_i32 s8, 0x42f
	v_writelane_b32 v247, s12, 21
	s_add_i32 s9, 16, 0x10e00
	s_add_i32 s10, 16, 0x10f00
	v_writelane_b32 v247, s13, 22
	v_cmp_gt_u32_e64 s[12:13], 32, v39
	v_sub_u32_e32 v111, v9, v11
	v_lshlrev_b32_e32 v9, 2, v32
	v_writelane_b32 v247, s12, 23
	v_add_u32_e32 v112, s9, v9
	v_add_u32_e32 v113, s10, v9
	v_writelane_b32 v247, s13, 24
	v_cmp_lt_i32_e64 s[12:13], s8, v32
	v_ashrrev_i32_e32 v9, 4, v32
	s_movk_i32 s8, 0x32f
	v_writelane_b32 v247, s12, 25
	v_cmp_gt_i32_e64 s[26:27], 3, v9
	v_lshlrev_b32_e32 v42, 7, v9
	v_writelane_b32 v247, s13, 26
	v_cmp_gt_i32_e64 s[12:13], 51, v9
	v_add_u32_e32 v9, 0x100, v32
	v_ashrrev_i32_e32 v11, 4, v9
	v_writelane_b32 v247, s12, 27
	v_mul_lo_u32 v13, v13, s11
	v_cmp_gt_i32_e64 s[34:35], 3, v11
	v_writelane_b32 v247, s13, 28
	v_cmp_lt_i32_e64 s[12:13], s8, v32
	s_movk_i32 s8, 0x22f
	v_lshlrev_b32_e32 v46, 7, v11
	v_writelane_b32 v247, s12, 29
	v_add3_u32 v109, 16, v13, v12
	v_lshl_add_u32 v8, v0, 2, 16
	v_writelane_b32 v247, s13, 30
	v_cmp_gt_i32_e64 s[12:13], 51, v11
	v_add_u32_e32 v11, 0x200, v32
	v_ashrrev_i32_e32 v12, 4, v11
	v_writelane_b32 v247, s12, 31
	v_cmp_gt_i32_e64 s[40:41], 3, v12
	v_lshlrev_b32_e32 v50, 7, v12
	v_writelane_b32 v247, s13, 32
	v_cmp_lt_i32_e64 s[12:13], s8, v32
	s_movk_i32 s8, 0x12f
	v_ashrrev_i32_e32 v22, 3, v32
	v_writelane_b32 v247, s12, 33
	v_ashrrev_i32_e32 v23, 3, v9
	v_lshlrev_b32_e32 v62, 6, v22
	v_writelane_b32 v247, s13, 34
	v_cmp_gt_i32_e64 s[12:13], 51, v12
	v_add_u32_e32 v12, 0x300, v32
	v_ashrrev_i32_e32 v13, 4, v12
	v_writelane_b32 v247, s12, 35
	v_cmp_gt_i32_e64 s[46:47], 3, v13
	v_lshlrev_b32_e32 v54, 7, v13
	v_writelane_b32 v247, s13, 36
	v_cmp_lt_i32_e64 s[12:13], s8, v32
	s_movk_i32 s8, 0x430
	v_cmp_gt_i32_e64 s[54:55], s8, v32
	v_writelane_b32 v247, s12, 37
	s_movk_i32 s8, 0x330
	v_cmp_gt_i32_e64 s[56:57], s8, v32
	v_writelane_b32 v247, s13, 38
	v_cmp_gt_i32_e64 s[12:13], 51, v13
	v_add_u32_e32 v13, 0x400, v32
	v_ashrrev_i32_e32 v14, 4, v13
	v_writelane_b32 v247, s12, 39
	v_cmp_gt_i32_e64 s[52:53], 3, v14
	v_lshlrev_b32_e32 v58, 7, v14
	v_writelane_b32 v247, s13, 40
	v_cmp_lt_i32_e64 s[12:13], 47, v32
	s_movk_i32 s8, 0x230
	v_lshlrev_b32_e32 v13, 5, v13
	v_writelane_b32 v247, s12, 41
	v_cmp_gt_i32_e64 s[58:59], s8, v32
	s_movk_i32 s8, 0x130
	v_writelane_b32 v247, s13, 42
	v_cmp_gt_i32_e64 s[12:13], 51, v14
	v_lshlrev_b32_e32 v14, 5, v32
	v_and_b32_e32 v14, 0xfffffe00, v14
	v_add_u32_e32 v114, v8, v14
	v_lshlrev_b32_e32 v14, 5, v9
	v_and_b32_e32 v14, 0xfffffe00, v14
	v_add_u32_e32 v115, v8, v14
	v_lshlrev_b32_e32 v14, 5, v11
	v_and_b32_e32 v14, 0xfffffe00, v14
	v_writelane_b32 v247, s12, 43
	v_add_u32_e32 v116, v8, v14
	v_lshlrev_b32_e32 v14, 5, v12
	v_writelane_b32 v247, s13, 44
	v_and_b32_e32 v14, 0xfffffe00, v14
	v_and_b32_e32 v13, 0xfffffe00, v13
	s_movk_i32 s12, 0x90
	v_cmp_gt_i32_e64 s[60:61], s8, v32
	v_add_u32_e32 v117, v8, v14
	v_add_u32_e32 v118, v8, v13
	v_mul_lo_u32 v8, v22, s12
	s_mov_b32 s8, 0x8600
	v_add3_u32 v119, v10, v8, s8
	v_mul_lo_u32 v8, v23, s12
	v_add3_u32 v120, v10, v8, s8
	v_ashrrev_i32_e32 v8, 3, v11
	v_mul_lo_u32 v9, v8, s12
	s_waitcnt vmcnt(6)
; __device__ __forceinline__ u16 f2bf(float f) { return (u16)(cvtpk(f, 0.f) & 0xffffu); }
; template <bool SIGNAL>
; __device__ __forceinline__ void phase2(const Params& p, unsigned char* smem, const int lo, const int hi, const int worker, const int nworkers) {
;     ...
;   for (int idx2 = lo + worker; idx2 < hi; idx2 += nworkers) {
;     const int bh = idx2 & 15, c = idx2 >> 4; const int it = bh * NCH + c; const int h = bh & 7;
;     ...
;     u16* Tg = TA + (size_t)it * 8704; u16* Ag = Tg + 4096; float* SCg = (float*)(Tg + 8192);
;     {
;       const int j = 32 * tj + l31; const float gcj = sgc[j];
; #pragma unroll
;       for (int r = 0; r < 16; ++r) {
;         const int i = 32 * ti + 8 * (r >> 2) + 4 * hf + (r & 3);
;         const float gci = sgc[i]; const float bi = sbeta[i];
;         const float dec = __expf(gci - gcj);
;         sM[i * 68 + j] = (j < i) ? bi * kk[r] * dec : 0.f;
;         Ag[i * 64 + j] = f2bf((j <= i) ? qk[r] * dec : 0.f);
;       }
;     }
	v_lshlrev_b32_e32 v66, 6, v8
	v_ashrrev_i32_e32 v8, 3, v12
	v_add3_u32 v121, v10, v9, s8
	v_mul_lo_u32 v9, v8, s12
	v_cmp_lt_i32_e64 s[12:13], v1, v20
	v_add3_u32 v122, v10, v9, s8
	v_or_b32_e32 v9, 1, v20
	v_writelane_b32 v247, s12, 45
	v_lshlrev_b32_e32 v10, 2, v9
	s_waitcnt vmcnt(5)
	v_lshl_or_b32 v72, v9, 6, v1
	v_writelane_b32 v247, s13, 46
	v_cmp_gt_i32_e64 s[12:13], v1, v9
	v_or_b32_e32 v9, 2, v20
	v_add_u32_e32 v125, s9, v10
	v_writelane_b32 v247, s12, 47
	v_add_u32_e32 v126, s10, v10
	v_lshlrev_b32_e32 v10, 2, v9
	v_writelane_b32 v247, s13, 48
	v_cmp_lt_i32_e64 s[12:13], v1, v9
	v_lshl_or_b32 v74, v9, 6, v1
	v_add_u32_e32 v127, s9, v10
	v_writelane_b32 v247, s12, 49
	v_add_u32_e32 v128, s10, v10
	v_lshlrev_b32_e32 v68, 6, v8
	v_writelane_b32 v247, s13, 50
	v_cmp_gt_i32_e64 s[12:13], v1, v9
	v_or_b32_e32 v9, 3, v20
	v_lshlrev_b32_e32 v10, 2, v9
	v_writelane_b32 v247, s12, 51
	s_waitcnt vmcnt(3)
	v_lshl_or_b32 v76, v9, 6, v1
	v_add_u32_e32 v129, s9, v10
	v_writelane_b32 v247, s13, 52
	v_cmp_lt_i32_e64 s[12:13], v1, v9
	v_add_u32_e32 v130, s10, v10
	v_lshlrev_b32_e32 v8, 2, v20
	v_writelane_b32 v247, s12, 53
	v_add_u32_e32 v123, s9, v8
	v_add_u32_e32 v124, s10, v8
	v_writelane_b32 v247, s13, 54
	v_cmp_gt_i32_e64 s[12:13], v1, v9
	v_or_b32_e32 v9, 8, v20
	v_lshlrev_b32_e32 v10, 2, v9
	v_add_u32_e32 v131, s9, v10
	v_add_u32_e32 v132, s10, v10
	v_or_b32_e32 v10, 9, v20
	v_lshlrev_b32_e32 v11, 2, v10
	v_add_u32_e32 v133, s9, v11
	v_add_u32_e32 v134, s10, v11
	v_or_b32_e32 v11, 10, v20
	v_lshlrev_b32_e32 v12, 2, v11
	v_add_u32_e32 v135, s9, v12
	v_add_u32_e32 v136, s10, v12
	v_or_b32_e32 v12, 11, v20
	v_lshlrev_b32_e32 v13, 2, v12
	v_add_u32_e32 v137, s9, v13
	v_add_u32_e32 v138, s10, v13
	v_or_b32_e32 v13, 16, v20
	v_lshlrev_b32_e32 v14, 2, v13
	v_add_u32_e32 v139, s9, v14
	v_add_u32_e32 v140, s10, v14
	v_or_b32_e32 v14, 17, v20
	v_lshlrev_b32_e32 v15, 2, v14
	v_add_u32_e32 v141, s9, v15
	v_add_u32_e32 v142, s10, v15
	v_or_b32_e32 v15, 18, v20
	v_lshlrev_b32_e32 v16, 2, v15
	v_add_u32_e32 v143, s9, v16
	v_add_u32_e32 v144, s10, v16
	v_or_b32_e32 v16, 19, v20
	v_lshlrev_b32_e32 v17, 2, v16
	v_add_u32_e32 v145, s9, v17
	v_add_u32_e32 v146, s10, v17
	v_or_b32_e32 v17, 24, v20
	v_lshlrev_b32_e32 v18, 2, v17
	v_add_u32_e32 v147, s9, v18
	v_add_u32_e32 v148, s10, v18
	v_or_b32_e32 v18, 25, v20
	v_lshlrev_b32_e32 v19, 2, v18
	v_writelane_b32 v247, s12, 55
	v_add_u32_e32 v149, s9, v19
	v_add_u32_e32 v150, s10, v19
	v_or_b32_e32 v19, 26, v20
	v_mul_lo_u32 v8, v20, s11
	v_cmp_gt_i32_e64 s[66:67], v1, v20
	v_lshl_or_b32 v70, v20, 6, v1
	v_writelane_b32 v247, s13, 56
	v_cmp_lt_i32_e64 s[12:13], v1, v9
	v_lshlrev_b32_e32 v24, 2, v19
	v_or_b32_e32 v20, 27, v20
	v_lshl_add_u32 v155, v22, 2, v21
	v_lshlrev_b32_e32 v22, 11, v2
	v_lshlrev_b32_e32 v3, 2, v39
	s_movk_i32 s2, 0x118
	v_lshlrev_b32_e32 v64, 6, v23
	v_writelane_b32 v247, s12, 57
	v_add_u32_e32 v151, s9, v24
	v_add_u32_e32 v152, s10, v24
	v_lshlrev_b32_e32 v24, 2, v20
	v_lshl_add_u32 v156, v23, 2, v21
	v_ashrrev_i32_e32 v23, 31, v22
	v_add_u32_e32 v104, s9, v3
	v_lshl_add_u32 v110, v1, 2, s9
	v_writelane_b32 v247, s13, 58
	v_add_u32_e32 v153, s9, v24
	s_add_i32 s9, s3, -16
	s_min_u32 s9, s9, 0xf8
	v_mad_u32_u24 v7, v39, s2, v7
	s_movk_i32 s2, 0x1100
	v_lshlrev_b64 v[22:23], 1, v[22:23]
	v_writelane_b32 v247, s9, 59
	s_add_u32 s9, s6, 0xf223840
	v_add3_u32 v157, v7, v5, s8
	v_mul_lo_u32 v7, v2, s2
	v_or_b32_e32 v22, v22, v3
	v_cmp_gt_u32_e32 vcc, 48, v39
	v_add_u32_e32 v105, s10, v3
	v_lshlrev_b32_e32 v107, 4, v2
	v_writelane_b32 v247, s9, 60
	s_addc_u32 s9, s7, 0
	v_or_b32_e32 v158, v7, v3
	v_lshl_or_b32 v160, v2, 13, v5
	v_lshl_add_u64 v[2:3], s[6:7], 0, v[22:23]
	s_mov_b64 s[6:7], 0x6090200
	v_writelane_b32 v247, s9, 61
	v_lshl_add_u64 v[102:103], v[2:3], 0, s[6:7]
	s_xor_b64 s[6:7], vcc, -1
	v_writelane_b32 v247, s6, 62
	s_add_i32 s2, 16, 0x10efc
	v_sub_u32_e32 v2, v4, v5
	v_writelane_b32 v247, s7, 63
	v_writelane_b32 v246, s2, 0
	v_cmp_gt_i32_e64 s[6:7], v1, v9
	v_lshl_or_b32 v78, v9, 6, v1
	v_lshl_or_b32 v80, v10, 6, v1
	v_writelane_b32 v246, s6, 1
	v_lshl_or_b32 v82, v11, 6, v1
	s_waitcnt vmcnt(2)
; __device__ __forceinline__ u16 f2bf(float f) { return (u16)(cvtpk(f, 0.f) & 0xffffu); }
; template <bool SIGNAL>
; __device__ __forceinline__ void phase2(const Params& p, unsigned char* smem, const int lo, const int hi, const int worker, const int nworkers) {
;     ...
;   for (int idx2 = lo + worker; idx2 < hi; idx2 += nworkers) {
;     const int bh = idx2 & 15, c = idx2 >> 4; const int it = bh * NCH + c; const int h = bh & 7;
;     ...
;     u16* Tg = TA + (size_t)it * 8704; u16* Ag = Tg + 4096; float* SCg = (float*)(Tg + 8192);
;     {
;       const int j = 32 * tj + l31; const float gcj = sgc[j];
; #pragma unroll
;       for (int r = 0; r < 16; ++r) {
;         const int i = 32 * ti + 8 * (r >> 2) + 4 * hf + (r & 3);
;         const float gci = sgc[i]; const float bi = sbeta[i];
;         const float dec = __expf(gci - gcj);
;         sM[i * 68 + j] = (j < i) ? bi * kk[r] * dec : 0.f;
;         Ag[i * 64 + j] = f2bf((j <= i) ? qk[r] * dec : 0.f);
;       }
;     }
	v_lshl_or_b32 v84, v12, 6, v1
	v_writelane_b32 v246, s7, 2
	v_cmp_lt_i32_e64 s[6:7], v1, v10
	v_lshl_or_b32 v86, v13, 6, v1
	s_waitcnt vmcnt(1)
	v_lshl_or_b32 v88, v14, 6, v1
	v_writelane_b32 v246, s6, 3
	v_lshl_or_b32 v90, v15, 6, v1
	s_waitcnt vmcnt(0)
	v_lshl_or_b32 v92, v16, 6, v1
	v_writelane_b32 v246, s7, 4
	v_cmp_gt_i32_e64 s[6:7], v1, v10
	v_lshl_or_b32 v94, v17, 6, v1
	v_lshl_or_b32 v96, v18, 6, v1
	v_writelane_b32 v246, s6, 5
	v_lshl_or_b32 v98, v19, 6, v1
	v_lshl_or_b32 v100, v20, 6, v1
	v_writelane_b32 v246, s7, 6
	v_cmp_lt_i32_e64 s[6:7], v1, v11
	v_add_u32_e32 v2, 16, v2
	v_cmp_gt_u32_e64 s[4:5], 64, v32
	v_writelane_b32 v246, s6, 7
	v_mov_b32_e32 v33, v35
	v_lshlrev_b32_e32 v106, 1, v39
	v_writelane_b32 v246, s7, 8
	v_cmp_gt_i32_e64 s[6:7], v1, v11
	v_ashrrev_i32_e32 v41, 31, v32
	v_mov_b32_e32 v40, v32
	v_writelane_b32 v246, s6, 9
	v_add_u32_e32 v44, 0xfffffe80, v42
	v_mov_b32_e32 v45, v35
	v_writelane_b32 v246, s7, 10
	v_cmp_lt_i32_e64 s[6:7], v1, v12
	v_ashrrev_i32_e32 v43, 31, v42
	v_add_u32_e32 v48, 0xfffffe80, v46
	v_writelane_b32 v246, s6, 11
	v_mov_b32_e32 v49, v35
	v_ashrrev_i32_e32 v47, 31, v46
	v_writelane_b32 v246, s7, 12
	v_cmp_gt_i32_e64 s[6:7], v1, v12
	v_add_u32_e32 v52, 0xfffffe80, v50
	v_mov_b32_e32 v53, v35
	v_writelane_b32 v246, s6, 13
	v_ashrrev_i32_e32 v51, 31, v50
	v_add_u32_e32 v56, 0xfffffe80, v54
	v_writelane_b32 v246, s7, 14
	v_cmp_lt_i32_e64 s[6:7], v1, v13
	v_mov_b32_e32 v57, v35
	v_ashrrev_i32_e32 v55, 31, v54
	v_writelane_b32 v246, s6, 15
	v_add_u32_e32 v60, 0xfffffe80, v58
	v_mov_b32_e32 v61, v35
	v_writelane_b32 v246, s7, 16
	v_cmp_gt_i32_e64 s[6:7], v1, v13
	v_ashrrev_i32_e32 v59, 31, v58
	v_cmp_gt_i32_e64 s[62:63], 48, v32
	v_writelane_b32 v246, s6, 17
	v_ashrrev_i32_e32 v63, 31, v62
	v_ashrrev_i32_e32 v65, 31, v64
	v_writelane_b32 v246, s7, 18
	v_cmp_lt_i32_e64 s[6:7], v1, v14
	v_ashrrev_i32_e32 v67, 31, v66
	v_ashrrev_i32_e32 v69, 31, v68
	v_writelane_b32 v246, s6, 19
	v_ashrrev_i32_e32 v71, 31, v70
	v_ashrrev_i32_e32 v73, 31, v72
	v_writelane_b32 v246, s7, 20
	v_cmp_gt_i32_e64 s[6:7], v1, v14
	v_ashrrev_i32_e32 v75, 31, v74
	v_ashrrev_i32_e32 v77, 31, v76
	v_writelane_b32 v246, s6, 21
	v_ashrrev_i32_e32 v79, 31, v78
	v_ashrrev_i32_e32 v81, 31, v80
	v_ashrrev_i32_e32 v83, 31, v82
	v_ashrrev_i32_e32 v85, 31, v84
	v_ashrrev_i32_e32 v87, 31, v86
	v_ashrrev_i32_e32 v89, 31, v88
	v_ashrrev_i32_e32 v91, 31, v90
	v_ashrrev_i32_e32 v93, 31, v92
	v_ashrrev_i32_e32 v95, 31, v94
	v_ashrrev_i32_e32 v97, 31, v96
	v_ashrrev_i32_e32 v99, 31, v98
	v_add_u32_e32 v154, s10, v24
	v_ashrrev_i32_e32 v101, 31, v100
	v_and_b32_e32 v159, 0xffffffc0, v32
	v_add_u32_e32 v161, 0x8600, v2
	v_lshlrev_b32_e32 v34, 1, v0
	s_add_i32 s87, 16, 0xca00
	s_mov_b32 s88, 0x800000
	v_add_u32_e32 v162, v6, v8
	v_mbcnt_hi_u32_b32 v163, -1, v219
	v_mov_b32_e32 v164, 0x300
	v_mov_b32_e32 v165, 0x3db504f3
	s_mov_b32 s2, s89
	v_writelane_b32 v246, s7, 22
	v_cmp_lt_i32_e64 s[10:11], v1, v15
	v_cmp_gt_i32_e64 s[12:13], v1, v15
	v_cmp_lt_i32_e64 s[14:15], v1, v16
	v_cmp_gt_i32_e64 s[16:17], v1, v16
	v_cmp_lt_i32_e64 s[18:19], v1, v17
	v_cmp_gt_i32_e64 s[20:21], v1, v17
	v_cmp_lt_i32_e64 s[6:7], v1, v18
	v_cmp_gt_i32_e64 s[8:9], v1, v18
	v_cmp_lt_i32_e64 s[22:23], v1, v19
	v_cmp_gt_i32_e64 s[24:25], v1, v19
	v_cmp_lt_i32_e64 s[28:29], v1, v20
	v_cmp_gt_i32_e64 s[30:31], v1, v20
	s_mov_b32 s64, 0x358637bd
	s_branch .LBB0_254
.LBB0_253:
	s_or_b64 exec, exec, s[38:39]
	v_readlane_b32 s36, v247, 59
	s_add_i32 s84, s36, s84
	s_add_i32 s2, s2, s36
	s_cmpk_lt_i32 s84, 0x810
	s_cbranch_scc0 .LBB0_310
